# v36 + DSA top-k bisection: compare masks rotated over three SGPR pairs and added as carry-in (2 VALU per key, no hazard nops)
# baseline (speedup 1.0000x reference)
; __device__ __forceinline__ unsigned wave_sum_u32(unsigned c) {
;     c += (unsigned)__builtin_amdgcn_update_dpp(0, (int)c, 0x128, 0xf, 0xf, false);
;     c += (unsigned)__builtin_amdgcn_update_dpp(0, (int)c, 0x124, 0xf, 0xf, false);
;     c += (unsigned)__builtin_amdgcn_update_dpp(0, (int)c, 0x122, 0xf, 0xf, false);
;     c += (unsigned)__builtin_amdgcn_update_dpp(0, (int)c, 0x121, 0xf, 0xf, false);
;     { const auto r = __builtin_amdgcn_permlane16_swap(c, c, false, false); c = r[0] + r[1]; }
;     { const auto r = __builtin_amdgcn_permlane32_swap(c, c, false, false); c = r[0] + r[1]; }
;     return c;
; }
; template <int NJ>
; __device__ __forceinline__ void dsa_select(LAS unsigned char* lds, int qs, int t, int lane) {
;     ...
;     unsigned theta = 1u; int need = t + 1;
;     if (t + 1 > 256) {
;         need = 256; theta = 0u;
;     ...
; #pragma unroll
;             for (int j = 0; j < NJ; ++j) c += (v[j] >= tr) ? 1u : 0u;
;             c = wave_sum_u32(c);
;             theta = (c >= 256u) ? tr : theta; }
;         theta = (unsigned)__builtin_amdgcn_readfirstlane((int)theta);
;     }
.LBB0_685:
	s_mov_b32 s0, 15
	s_mov_b32 s17, 0
.Lbis2_686:
	s_lshl_b32 s2, 1, s0
	s_or_b32 s2, s2, s17
	v_mov_b32_e32 v98, s2
	v_mov_b32_e32 v99, 0
	v_cmp_ge_u32_e64 vcc, v65, v98
	v_cmp_ge_u32_e64 s[98:99], v66, v98
	v_cmp_ge_u32_e64 s[100:101], v67, v98
	v_addc_co_u32_e64 v99, vcc, v99, 0, vcc
	v_cmp_ge_u32_e64 vcc, v68, v98
	v_addc_co_u32_e64 v99, s[98:99], v99, 0, s[98:99]
	v_cmp_ge_u32_e64 s[98:99], v69, v98
	v_addc_co_u32_e64 v99, s[100:101], v99, 0, s[100:101]
	v_cmp_ge_u32_e64 s[100:101], v70, v98
	v_addc_co_u32_e64 v99, vcc, v99, 0, vcc
	v_cmp_ge_u32_e64 vcc, v71, v98
	v_addc_co_u32_e64 v99, s[98:99], v99, 0, s[98:99]
	v_cmp_ge_u32_e64 s[98:99], v72, v98
	v_addc_co_u32_e64 v99, s[100:101], v99, 0, s[100:101]
	v_cmp_ge_u32_e64 s[100:101], v73, v98
	v_addc_co_u32_e64 v99, vcc, v99, 0, vcc
	v_cmp_ge_u32_e64 vcc, v74, v98
	v_addc_co_u32_e64 v99, s[98:99], v99, 0, s[98:99]
	v_cmp_ge_u32_e64 s[98:99], v75, v98
	v_addc_co_u32_e64 v99, s[100:101], v99, 0, s[100:101]
	v_cmp_ge_u32_e64 s[100:101], v76, v98
	v_addc_co_u32_e64 v99, vcc, v99, 0, vcc
	v_cmp_ge_u32_e64 vcc, v77, v98
	v_addc_co_u32_e64 v99, s[98:99], v99, 0, s[98:99]
	v_cmp_ge_u32_e64 s[98:99], v78, v98
	v_addc_co_u32_e64 v99, s[100:101], v99, 0, s[100:101]
	v_cmp_ge_u32_e64 s[100:101], v79, v98
	v_addc_co_u32_e64 v99, vcc, v99, 0, vcc
	v_cmp_ge_u32_e64 vcc, v80, v98
	v_addc_co_u32_e64 v99, s[98:99], v99, 0, s[98:99]
	v_cmp_ge_u32_e64 s[98:99], v81, v98
	v_addc_co_u32_e64 v99, s[100:101], v99, 0, s[100:101]
	v_cmp_ge_u32_e64 s[100:101], v82, v98
	v_addc_co_u32_e64 v99, vcc, v99, 0, vcc
	v_cmp_ge_u32_e64 vcc, v83, v98
	v_addc_co_u32_e64 v99, s[98:99], v99, 0, s[98:99]
	v_cmp_ge_u32_e64 s[98:99], v84, v98
	v_addc_co_u32_e64 v99, s[100:101], v99, 0, s[100:101]
	v_cmp_ge_u32_e64 s[100:101], v85, v98
	v_addc_co_u32_e64 v99, vcc, v99, 0, vcc
	v_cmp_ge_u32_e64 vcc, v86, v98
	v_addc_co_u32_e64 v99, s[98:99], v99, 0, s[98:99]
	v_cmp_ge_u32_e64 s[98:99], v87, v98
	v_addc_co_u32_e64 v99, s[100:101], v99, 0, s[100:101]
	v_cmp_ge_u32_e64 s[100:101], v88, v98
	v_addc_co_u32_e64 v99, vcc, v99, 0, vcc
	v_cmp_ge_u32_e64 vcc, v89, v98
	v_addc_co_u32_e64 v99, s[98:99], v99, 0, s[98:99]
	v_cmp_ge_u32_e64 s[98:99], v90, v98
	v_addc_co_u32_e64 v99, s[100:101], v99, 0, s[100:101]
	v_cmp_ge_u32_e64 s[100:101], v91, v98
	v_addc_co_u32_e64 v99, vcc, v99, 0, vcc
	v_cmp_ge_u32_e64 vcc, v92, v98
	v_addc_co_u32_e64 v99, s[98:99], v99, 0, s[98:99]
	v_cmp_ge_u32_e64 s[98:99], v93, v98
	v_addc_co_u32_e64 v99, s[100:101], v99, 0, s[100:101]
	v_cmp_ge_u32_e64 s[100:101], v94, v98
	v_addc_co_u32_e64 v99, vcc, v99, 0, vcc
	v_cmp_ge_u32_e64 vcc, v95, v98
	v_addc_co_u32_e64 v99, s[98:99], v99, 0, s[98:99]
	v_cmp_ge_u32_e64 s[98:99], v96, v98
	v_addc_co_u32_e64 v99, s[100:101], v99, 0, s[100:101]
	s_nop 0
	v_addc_co_u32_e64 v99, vcc, v99, 0, vcc
	s_nop 0
	v_addc_co_u32_e64 v99, s[98:99], v99, 0, s[98:99]
	s_nop 1
	v_add_u32_dpp v99, v99, v99 row_ror:8 row_mask:0xf bank_mask:0xf bound_ctrl:1
	s_nop 1
	v_add_u32_dpp v99, v99, v99 row_ror:4 row_mask:0xf bank_mask:0xf bound_ctrl:1
	s_nop 1
	v_add_u32_dpp v99, v99, v99 row_ror:2 row_mask:0xf bank_mask:0xf bound_ctrl:1
	s_nop 1
	v_add_u32_dpp v99, v99, v99 row_ror:1 row_mask:0xf bank_mask:0xf bound_ctrl:1
	v_mov_b32_e32 v100, v99
	s_nop 1
	v_permlane16_swap_b32_e32 v99, v100
	v_add_u32_e32 v99, v99, v100
	v_mov_b32_e32 v100, v99
	s_nop 1
	v_permlane32_swap_b32_e32 v99, v100
	v_add_u32_e32 v99, v99, v100
	s_nop 0
	v_readfirstlane_b32 s99, v99
	s_nop 0
	s_cmp_gt_u32 s99, 0xff
	s_cselect_b32 s17, s2, s17
	s_add_i32 s0, s0, -1
	s_cmp_lt_i32 s0, 0
	s_cbranch_scc0 .Lbis2_686
	s_movk_i32 s2, 0x100
	s_branch .LBB0_693

; __device__ __forceinline__ unsigned wave_sum_u32(unsigned c) {
;     c += (unsigned)__builtin_amdgcn_update_dpp(0, (int)c, 0x128, 0xf, 0xf, false);
;     c += (unsigned)__builtin_amdgcn_update_dpp(0, (int)c, 0x124, 0xf, 0xf, false);
;     c += (unsigned)__builtin_amdgcn_update_dpp(0, (int)c, 0x122, 0xf, 0xf, false);
;     c += (unsigned)__builtin_amdgcn_update_dpp(0, (int)c, 0x121, 0xf, 0xf, false);
;     { const auto r = __builtin_amdgcn_permlane16_swap(c, c, false, false); c = r[0] + r[1]; }
;     { const auto r = __builtin_amdgcn_permlane32_swap(c, c, false, false); c = r[0] + r[1]; }
;     return c;
; }
; template <int NJ>
; __device__ __forceinline__ void dsa_select(LAS unsigned char* lds, int qs, int t, int lane) {
;     ...
;     unsigned theta = 1u; int need = t + 1;
;     if (t + 1 > 256) {
;         need = 256; theta = 0u;
;     ...
; #pragma unroll
;             for (int j = 0; j < NJ; ++j) c += (v[j] >= tr) ? 1u : 0u;
;             c = wave_sum_u32(c);
;             theta = (c >= 256u) ? tr : theta; }
;         theta = (unsigned)__builtin_amdgcn_readfirstlane((int)theta);
;     }
.LBB0_877:
	s_mov_b32 s0, 15
	s_mov_b32 s2, 0
.Lbis2_878:
	s_lshl_b32 s14, 1, s0
	s_or_b32 s14, s14, s2
	v_mov_b32_e32 v90, s14
	v_mov_b32_e32 v91, 0
	v_cmp_ge_u32_e64 vcc, v65, v90
	v_cmp_ge_u32_e64 s[98:99], v66, v90
	v_cmp_ge_u32_e64 s[100:101], v67, v90
	v_addc_co_u32_e64 v91, vcc, v91, 0, vcc
	v_cmp_ge_u32_e64 vcc, v68, v90
	v_addc_co_u32_e64 v91, s[98:99], v91, 0, s[98:99]
	v_cmp_ge_u32_e64 s[98:99], v69, v90
	v_addc_co_u32_e64 v91, s[100:101], v91, 0, s[100:101]
	v_cmp_ge_u32_e64 s[100:101], v70, v90
	v_addc_co_u32_e64 v91, vcc, v91, 0, vcc
	v_cmp_ge_u32_e64 vcc, v71, v90
	v_addc_co_u32_e64 v91, s[98:99], v91, 0, s[98:99]
	v_cmp_ge_u32_e64 s[98:99], v72, v90
	v_addc_co_u32_e64 v91, s[100:101], v91, 0, s[100:101]
	v_cmp_ge_u32_e64 s[100:101], v73, v90
	v_addc_co_u32_e64 v91, vcc, v91, 0, vcc
	v_cmp_ge_u32_e64 vcc, v74, v90
	v_addc_co_u32_e64 v91, s[98:99], v91, 0, s[98:99]
	v_cmp_ge_u32_e64 s[98:99], v75, v90
	v_addc_co_u32_e64 v91, s[100:101], v91, 0, s[100:101]
	v_cmp_ge_u32_e64 s[100:101], v76, v90
	v_addc_co_u32_e64 v91, vcc, v91, 0, vcc
	v_cmp_ge_u32_e64 vcc, v77, v90
	v_addc_co_u32_e64 v91, s[98:99], v91, 0, s[98:99]
	v_cmp_ge_u32_e64 s[98:99], v78, v90
	v_addc_co_u32_e64 v91, s[100:101], v91, 0, s[100:101]
	v_cmp_ge_u32_e64 s[100:101], v79, v90
	v_addc_co_u32_e64 v91, vcc, v91, 0, vcc
	v_cmp_ge_u32_e64 vcc, v80, v90
	v_addc_co_u32_e64 v91, s[98:99], v91, 0, s[98:99]
	v_cmp_ge_u32_e64 s[98:99], v81, v90
	v_addc_co_u32_e64 v91, s[100:101], v91, 0, s[100:101]
	v_cmp_ge_u32_e64 s[100:101], v82, v90
	v_addc_co_u32_e64 v91, vcc, v91, 0, vcc
	v_cmp_ge_u32_e64 vcc, v83, v90
	v_addc_co_u32_e64 v91, s[98:99], v91, 0, s[98:99]
	v_cmp_ge_u32_e64 s[98:99], v84, v90
	v_addc_co_u32_e64 v91, s[100:101], v91, 0, s[100:101]
	v_cmp_ge_u32_e64 s[100:101], v85, v90
	v_addc_co_u32_e64 v91, vcc, v91, 0, vcc
	v_cmp_ge_u32_e64 vcc, v86, v90
	v_addc_co_u32_e64 v91, s[98:99], v91, 0, s[98:99]
	v_cmp_ge_u32_e64 s[98:99], v87, v90
	v_addc_co_u32_e64 v91, s[100:101], v91, 0, s[100:101]
	v_cmp_ge_u32_e64 s[100:101], v88, v90
	v_addc_co_u32_e64 v91, vcc, v91, 0, vcc
	s_nop 0
	v_addc_co_u32_e64 v91, s[98:99], v91, 0, s[98:99]
	s_nop 0
	v_addc_co_u32_e64 v91, s[100:101], v91, 0, s[100:101]
	s_nop 1
	v_add_u32_dpp v91, v91, v91 row_ror:8 row_mask:0xf bank_mask:0xf bound_ctrl:1
	s_nop 1
	v_add_u32_dpp v91, v91, v91 row_ror:4 row_mask:0xf bank_mask:0xf bound_ctrl:1
	s_nop 1
	v_add_u32_dpp v91, v91, v91 row_ror:2 row_mask:0xf bank_mask:0xf bound_ctrl:1
	s_nop 1
	v_add_u32_dpp v91, v91, v91 row_ror:1 row_mask:0xf bank_mask:0xf bound_ctrl:1
	v_mov_b32_e32 v92, v91
	s_nop 1
	v_permlane16_swap_b32_e32 v91, v92
	v_add_u32_e32 v91, v91, v92
	v_mov_b32_e32 v92, v91
	s_nop 1
	v_permlane32_swap_b32_e32 v91, v92
	v_add_u32_e32 v91, v91, v92
	s_nop 0
	v_readfirstlane_b32 s99, v91
	s_nop 0
	s_cmp_gt_u32 s99, 0xff
	s_cselect_b32 s2, s14, s2
	s_add_i32 s0, s0, -1
	s_cmp_lt_i32 s0, 0
	s_cbranch_scc0 .Lbis2_878
	s_movk_i32 s14, 0x100
	s_branch .LBB0_883

; __device__ __forceinline__ unsigned wave_sum_u32(unsigned c) {
;     c += (unsigned)__builtin_amdgcn_update_dpp(0, (int)c, 0x128, 0xf, 0xf, false);
;     c += (unsigned)__builtin_amdgcn_update_dpp(0, (int)c, 0x124, 0xf, 0xf, false);
;     c += (unsigned)__builtin_amdgcn_update_dpp(0, (int)c, 0x122, 0xf, 0xf, false);
;     c += (unsigned)__builtin_amdgcn_update_dpp(0, (int)c, 0x121, 0xf, 0xf, false);
;     { const auto r = __builtin_amdgcn_permlane16_swap(c, c, false, false); c = r[0] + r[1]; }
;     { const auto r = __builtin_amdgcn_permlane32_swap(c, c, false, false); c = r[0] + r[1]; }
;     return c;
; }
; template <int NJ>
; __device__ __forceinline__ void dsa_select(LAS unsigned char* lds, int qs, int t, int lane) {
;     ...
;     unsigned theta = 1u; int need = t + 1;
;     if (t + 1 > 256) {
;         need = 256; theta = 0u;
;     ...
; #pragma unroll
;             for (int j = 0; j < NJ; ++j) c += (v[j] >= tr) ? 1u : 0u;
;             c = wave_sum_u32(c);
;             theta = (c >= 256u) ? tr : theta; }
;         theta = (unsigned)__builtin_amdgcn_readfirstlane((int)theta);
;     }
.Lbis2_1021:
	s_lshl_b32 s14, 1, s0
	s_or_b32 s14, s14, s2
	v_mov_b32_e32 v83, s14
	v_mov_b32_e32 v84, 0
	v_cmp_ge_u32_e64 vcc, v65, v83
	v_cmp_ge_u32_e64 s[98:99], v66, v83
	v_cmp_ge_u32_e64 s[100:101], v67, v83
	v_addc_co_u32_e64 v84, vcc, v84, 0, vcc
	v_cmp_ge_u32_e64 vcc, v68, v83
	v_addc_co_u32_e64 v84, s[98:99], v84, 0, s[98:99]
	v_cmp_ge_u32_e64 s[98:99], v69, v83
	v_addc_co_u32_e64 v84, s[100:101], v84, 0, s[100:101]
	v_cmp_ge_u32_e64 s[100:101], v70, v83
	v_addc_co_u32_e64 v84, vcc, v84, 0, vcc
	v_cmp_ge_u32_e64 vcc, v71, v83
	v_addc_co_u32_e64 v84, s[98:99], v84, 0, s[98:99]
	v_cmp_ge_u32_e64 s[98:99], v72, v83
	v_addc_co_u32_e64 v84, s[100:101], v84, 0, s[100:101]
	v_cmp_ge_u32_e64 s[100:101], v73, v83
	v_addc_co_u32_e64 v84, vcc, v84, 0, vcc
	v_cmp_ge_u32_e64 vcc, v74, v83
	v_addc_co_u32_e64 v84, s[98:99], v84, 0, s[98:99]
	v_cmp_ge_u32_e64 s[98:99], v75, v83
	v_addc_co_u32_e64 v84, s[100:101], v84, 0, s[100:101]
	v_cmp_ge_u32_e64 s[100:101], v76, v83
	v_addc_co_u32_e64 v84, vcc, v84, 0, vcc
	v_cmp_ge_u32_e64 vcc, v77, v83
	v_addc_co_u32_e64 v84, s[98:99], v84, 0, s[98:99]
	v_cmp_ge_u32_e64 s[98:99], v78, v83
	v_addc_co_u32_e64 v84, s[100:101], v84, 0, s[100:101]
	v_cmp_ge_u32_e64 s[100:101], v79, v83
	v_addc_co_u32_e64 v84, vcc, v84, 0, vcc
	v_cmp_ge_u32_e64 vcc, v80, v83
	v_addc_co_u32_e64 v84, s[98:99], v84, 0, s[98:99]
	s_nop 0
	v_addc_co_u32_e64 v84, s[100:101], v84, 0, s[100:101]
	s_nop 0
	v_addc_co_u32_e64 v84, vcc, v84, 0, vcc
	s_nop 1
	v_add_u32_dpp v84, v84, v84 row_ror:8 row_mask:0xf bank_mask:0xf bound_ctrl:1
	s_nop 1
	v_add_u32_dpp v84, v84, v84 row_ror:4 row_mask:0xf bank_mask:0xf bound_ctrl:1
	s_nop 1
	v_add_u32_dpp v84, v84, v84 row_ror:2 row_mask:0xf bank_mask:0xf bound_ctrl:1
	s_nop 1
	v_add_u32_dpp v84, v84, v84 row_ror:1 row_mask:0xf bank_mask:0xf bound_ctrl:1
	v_mov_b32_e32 v85, v84
	s_nop 1
	v_permlane16_swap_b32_e32 v84, v85
	v_add_u32_e32 v84, v84, v85
	v_mov_b32_e32 v85, v84
	s_nop 1
	v_permlane32_swap_b32_e32 v84, v85
	v_add_u32_e32 v84, v84, v85
	s_nop 0
	v_readfirstlane_b32 s99, v84
	s_nop 0
	s_cmp_gt_u32 s99, 0xff
	s_cselect_b32 s2, s14, s2
	s_add_i32 s0, s0, -1
	s_cmp_lt_i32 s0, 0
	s_cbranch_scc0 .Lbis2_1021
	s_movk_i32 s14, 0x100
	s_branch .LBB0_1026

; __device__ __forceinline__ unsigned wave_sum_u32(unsigned c) {
;     c += (unsigned)__builtin_amdgcn_update_dpp(0, (int)c, 0x128, 0xf, 0xf, false);
;     c += (unsigned)__builtin_amdgcn_update_dpp(0, (int)c, 0x124, 0xf, 0xf, false);
;     c += (unsigned)__builtin_amdgcn_update_dpp(0, (int)c, 0x122, 0xf, 0xf, false);
;     c += (unsigned)__builtin_amdgcn_update_dpp(0, (int)c, 0x121, 0xf, 0xf, false);
;     { const auto r = __builtin_amdgcn_permlane16_swap(c, c, false, false); c = r[0] + r[1]; }
;     { const auto r = __builtin_amdgcn_permlane32_swap(c, c, false, false); c = r[0] + r[1]; }
;     return c;
; }
; template <int NJ>
; __device__ __forceinline__ void dsa_select(LAS unsigned char* lds, int qs, int t, int lane) {
;     ...
;     unsigned theta = 1u; int need = t + 1;
;     if (t + 1 > 256) {
;         need = 256; theta = 0u;
;     ...
; #pragma unroll
;             for (int j = 0; j < NJ; ++j) c += (v[j] >= tr) ? 1u : 0u;
;             c = wave_sum_u32(c);
;             theta = (c >= 256u) ? tr : theta; }
;         theta = (unsigned)__builtin_amdgcn_readfirstlane((int)theta);
;     }
.Lbis2_1117:
	s_lshl_b32 s14, 1, s0
	s_or_b32 s14, s14, s2
	v_mov_b32_e32 v75, s14
	v_mov_b32_e32 v76, 0
	v_cmp_ge_u32_e64 vcc, v65, v75
	v_cmp_ge_u32_e64 s[98:99], v66, v75
	v_cmp_ge_u32_e64 s[100:101], v67, v75
	v_addc_co_u32_e64 v76, vcc, v76, 0, vcc
	v_cmp_ge_u32_e64 vcc, v68, v75
	v_addc_co_u32_e64 v76, s[98:99], v76, 0, s[98:99]
	v_cmp_ge_u32_e64 s[98:99], v69, v75
	v_addc_co_u32_e64 v76, s[100:101], v76, 0, s[100:101]
	v_cmp_ge_u32_e64 s[100:101], v70, v75
	v_addc_co_u32_e64 v76, vcc, v76, 0, vcc
	v_cmp_ge_u32_e64 vcc, v71, v75
	v_addc_co_u32_e64 v76, s[98:99], v76, 0, s[98:99]
	v_cmp_ge_u32_e64 s[98:99], v72, v75
	v_addc_co_u32_e64 v76, s[100:101], v76, 0, s[100:101]
	s_nop 0
	v_addc_co_u32_e64 v76, vcc, v76, 0, vcc
	s_nop 0
	v_addc_co_u32_e64 v76, s[98:99], v76, 0, s[98:99]
	s_nop 1
	v_add_u32_dpp v76, v76, v76 row_ror:8 row_mask:0xf bank_mask:0xf bound_ctrl:1
	s_nop 1
	v_add_u32_dpp v76, v76, v76 row_ror:4 row_mask:0xf bank_mask:0xf bound_ctrl:1
	s_nop 1
	v_add_u32_dpp v76, v76, v76 row_ror:2 row_mask:0xf bank_mask:0xf bound_ctrl:1
	s_nop 1
	v_add_u32_dpp v76, v76, v76 row_ror:1 row_mask:0xf bank_mask:0xf bound_ctrl:1
	v_mov_b32_e32 v74, v76
	s_nop 1
	v_permlane16_swap_b32_e32 v76, v74
	v_add_u32_e32 v76, v76, v74
	v_mov_b32_e32 v74, v76
	s_nop 1
	v_permlane32_swap_b32_e32 v76, v74
	v_add_u32_e32 v76, v76, v74
	s_nop 0
	v_readfirstlane_b32 s99, v76
	s_nop 0
	s_cmp_gt_u32 s99, 0xff
	s_cselect_b32 s2, s14, s2
	s_add_i32 s0, s0, -1
	s_cmp_lt_i32 s0, 0
	s_cbranch_scc0 .Lbis2_1117
	s_movk_i32 s14, 0x100
	s_branch .LBB0_1122
